# prologue: weight-conversion items handed out in reverse wave order so the workgroups that also compute ada get one item fewer
# speedup vs baseline: 1.0056x; 1.0056x over previous
.LBB0_28:
	s_lshl_b32 s0, s14, 3
	s_add_i32 s4, s0, s15
	s_lshl_b32 s98, s17, 3
	s_sub_i32 s98, s98, 1
	s_sub_i32 s4, s98, s4
	s_cmpk_gt_i32 s4, 0x38ff
	s_barrier
	s_cbranch_scc1 .LBB0_59
	s_mulk_i32 s15, 0x2200
	v_lshrrev_b32_e32 v34, 5, v16
	v_lshlrev_b32_e32 v0, 2, v0
	s_add_i32 s0, s15, 0
	v_and_b32_e32 v32, 0x7c, v0
	v_mul_u32_u24_e32 v0, 0x84, v34
	v_add3_u32 v46, s0, v32, v0
	v_lshlrev_b32_e32 v0, 3, v16
	v_and_b32_e32 v0, 56, v0
	v_mul_u32_u24_e32 v4, 0x84, v0
	v_lshlrev_b32_e32 v0, 1, v0
	v_mov_b32_e32 v1, 0
	v_lshrrev_b32_e32 v35, 3, v16
	v_lshl_add_u64 v[16:17], s[2:3], 0, v[0:1]
	s_mov_b64 s[2:3], 0x2d00000
	v_lshl_add_u64 v[2:3], v[16:17], 0, s[2:3]
	v_lshlrev_b32_e32 v0, 2, v35
	s_mov_b64 s[2:3], 0x2b00000
	v_add3_u32 v0, s0, v4, v0
	v_lshl_add_u64 v[4:5], v[16:17], 0, s[2:3]
	s_mov_b64 s[2:3], 0x2900000
	v_lshl_add_u64 v[6:7], v[16:17], 0, s[2:3]
	s_mov_b64 s[2:3], 0x3a00000
	v_lshl_add_u64 v[8:9], v[16:17], 0, s[2:3]
	s_mov_b64 s[2:3], 0x1100000
	v_lshl_add_u64 v[10:11], v[16:17], 0, s[2:3]
	s_mov_b64 s[2:3], 0x2f00000
	v_lshl_add_u64 v[12:13], v[16:17], 0, s[2:3]
	s_mov_b64 s[2:3], 0x600000
	v_readlane_b32 s36, v252, 2
	v_lshl_add_u64 v[14:15], v[16:17], 0, s[2:3]
	s_mov_b64 s[2:3], 0x1700000
	v_mov_b32_e32 v33, v1
	v_readlane_b32 s37, v252, 3
	v_readlane_b32 s38, v252, 4
	v_readlane_b32 s39, v252, 5
	v_readlane_b32 s40, v252, 6
	v_readlane_b32 s41, v252, 7
	v_readlane_b32 s42, v252, 8
	v_readlane_b32 s43, v252, 9
	v_readlane_b32 s44, v252, 10
	v_readlane_b32 s45, v252, 11
	v_readlane_b32 s46, v252, 12
	v_readlane_b32 s47, v252, 13
	v_readlane_b32 s48, v252, 14
	v_readlane_b32 s49, v252, 15
	v_readlane_b32 s50, v252, 16
	v_readlane_b32 s51, v252, 17
	s_lshl_b32 s0, s4, 1
	s_lshl_b32 s5, s17, 3
	s_mov_b32 s1, 0
	v_or_b32_e32 v36, 8, v35
	v_or_b32_e32 v37, 16, v35
	v_or_b32_e32 v38, 24, v35
	v_lshl_add_u64 v[16:17], v[16:17], 0, s[2:3]
	v_lshl_add_u64 v[18:19], s[48:49], 0, v[32:33]
	v_lshl_add_u64 v[20:21], s[46:47], 0, v[32:33]
	v_lshl_add_u64 v[22:23], s[40:41], 0, v[32:33]
	v_lshl_add_u64 v[24:25], s[60:61], 0, v[32:33]
	v_lshl_add_u64 v[26:27], s[76:77], 0, v[32:33]
	v_lshl_add_u64 v[28:29], s[50:51], 0, v[32:33]
	v_lshl_add_u64 v[30:31], s[74:75], 0, v[32:33]
	v_lshl_add_u64 v[32:33], s[78:79], 0, v[32:33]
	s_lshl_b32 s8, s4, 5
	s_lshl_b32 s9, s17, 8
	s_lshl_b32 s14, s4, 6
	s_lshl_b32 s15, s17, 9
	s_add_i32 s16, s0, 0x1b000
	s_lshl_b32 s17, s17, 4
	s_mov_b32 s18, 0x16000
	s_mov_b32 s19, 0x2c000
	s_mov_b32 s20, 0xb000
	s_mov_b32 s21, 0x21000
	s_mov_b32 s22, 0x37000
	s_mov_b32 s23, 0x42000
	s_mov_b32 s24, 0x4d000
	s_mov_b32 s25, 0x58000
	s_mov_b32 s26, 0x63000
	s_mov_b32 s27, 0x6e000
	s_mov_b32 s28, 0x79000
	s_mov_b32 s29, 0x84000
	s_mov_b32 s30, 0x8f000
	s_mov_b32 s31, 0x9a000
	s_mov_b32 s34, 0xa5000
	s_mov_b32 s35, 0xb0000
	s_mov_b32 s36, 0xbb000
	s_mov_b32 s37, 0xc6000
	s_mov_b32 s38, 0xd1000
	s_mov_b32 s39, 0xdc000
	s_mov_b32 s40, 0xe7000
	s_mov_b32 s41, 0xf2000
	s_mov_b32 s42, 0xfd000
	s_mov_b32 s43, 0x108000
	s_mov_b32 s44, 0x113000
	s_mov_b32 s45, 0x11e000
	s_mov_b32 s46, 0x129000
	s_mov_b32 s47, 0x134000
	s_mov_b32 s48, 0x13f000
	s_mov_b32 s49, 0x14a000
	s_mov_b32 s51, 0x155000
	s_mov_b32 s52, 0x9000
	v_add_u32_e32 v39, 0xc000, v46
	v_add_u32_e32 v40, 0xc400, v46
	v_add_u32_e32 v41, 0xc800, v46
	v_add_u32_e32 v42, 0xcc00, v46
	v_add_u32_e32 v43, 0xd000, v46
	v_add_u32_e32 v44, 0xd400, v46
	v_add_u32_e32 v45, 0xd800, v46
	v_add_u32_e32 v46, 0xdc00, v46
	v_add_u32_e32 v47, 0xc000, v0
	s_branch .LBB0_31
